# nt cache hint on once-read streams: conv phase loads, out-proj epilogue f32 x loads, final norm loads and its f32 output stores
# baseline (speedup 1.0000x reference)
; __device__ __forceinline__ unsigned pk2(float lo, float hi) { return f2bf(lo) | (f2bf(hi) << 16); }
; __device__ __forceinline__ void conv_phase(const bf16* bcu, const float* cw, bf16* Y, int gtid, int gthreads) {
;     constexpr int CH = 16, NCG = D / 8, NITEM = (M / CH) * NCG;
;     for (int it = gtid; it < NITEM; it += gthreads) {
;         const int cg_ = it % NCG, chunk = it / NCG, col = cg_ * 8; const size_t t0 = (size_t)chunk * CH; const int s0 = (int)(t0 % SEQ);
;         float w0[8], w1[8], w2[8];
; #pragma unroll
;         for (int e = 0; e < 8; ++e) { w0[e] = cw[col + e]; w1[e] = cw[D + col + e]; w2[e] = cw[2 * D + col + e]; }
;         float prev[8], cur[8], nxt[8];
;         if (s0 > 0) load_cu(bcu, t0 - 1, col, prev); else {
; #pragma unroll
;             for (int e = 0; e < 8; ++e) prev[e] = 0.f; }
;         load_cu(bcu, t0, col, cur);
; #pragma unroll 4
;         for (int i = 0; i < CH; ++i) {
;             const size_t t = t0 + i;
;             if (s0 + i + 1 < SEQ) load_cu(bcu, t + 1, col, nxt); else {
; #pragma unroll
;                 for (int e = 0; e < 8; ++e) nxt[e] = 0.f; }
;             const v4u bb = *(const v4u*)(bcu + t * (size_t)D + col);
;             float g[8] = {bflo(bb.x), bfhi(bb.x), bflo(bb.y), bfhi(bb.y), bflo(bb.z), bfhi(bb.z), bflo(bb.w), bfhi(bb.w)};
;             float y[8];
; #pragma unroll
;             for (int e = 0; e < 8; ++e) { y[e] = g[e] * (w0[e] * prev[e] + w1[e] * cur[e] + w2[e] * nxt[e]); prev[e] = cur[e]; cur[e] = nxt[e]; }
;             v4u o; o.x = pk2(y[0], y[1]); o.y = pk2(y[2], y[3]); o.z = pk2(y[4], y[5]); o.w = pk2(y[6], y[7]);
;             *(v4u*)(Y + t * (size_t)D + col) = o;
.LBB0_170:
	v_ashrrev_i32_e32 v1, 31, v54
	v_add_u32_sdwa v1, v54, v1 dst_sel:DWORD dst_unused:UNUSED_PAD src0_sel:DWORD src1_sel:BYTE_3
	v_ashrrev_i32_e32 v2, 8, v1
	v_mul_i32_i24_e32 v1, 0x100, v2
	v_sub_u32_e32 v1, v54, v1
	v_lshlrev_b32_e32 v4, 3, v1
	v_ashrrev_i32_e32 v5, 31, v4
	v_lshl_add_u64 v[6:7], v[4:5], 2, s[44:45]
	v_add_co_u32_e32 v18, vcc, s1, v6
	v_lshl_add_u64 v[8:9], v[6:7], 0, s[14:15]
	s_nop 0
	v_addc_co_u32_e32 v19, vcc, 0, v7, vcc
	v_lshl_add_u64 v[30:31], v[6:7], 0, s[46:47]
	global_load_dwordx4 v[10:13], v[6:7], off offset:16 nt
	global_load_dwordx4 v[14:17], v[6:7], off nt
	v_add_co_u32_e32 v6, vcc, 0x4000, v6
	v_lshlrev_b32_e32 v1, 4, v2
	s_nop 0
	v_addc_co_u32_e32 v7, vcc, 0, v7, vcc
	global_load_dwordx4 v[18:21], v[18:19], off nt
	s_nop 0
	global_load_dwordx4 v[22:25], v[6:7], off nt
	global_load_dwordx4 v[26:29], v[8:9], off offset:16 nt
	s_nop 0
	global_load_dwordx4 v[30:33], v[30:31], off offset:16 nt
	v_ashrrev_i32_e32 v3, 31, v2
	v_and_b32_e32 v1, 0xff0, v1
	v_cmp_ne_u32_e32 vcc, 0, v1
	v_lshlrev_b64 v[2:3], 16, v[2:3]
	v_mov_b32_e32 v36, v0
	v_mov_b32_e32 v37, v0
	v_mov_b32_e32 v38, v0
	v_mov_b32_e32 v39, v0
	v_mov_b32_e32 v40, v0
	v_mov_b32_e32 v41, v0
	v_mov_b32_e32 v42, v0
	v_mov_b32_e32 v43, v0
	s_and_saveexec_b64 s[48:49], vcc
	s_cbranch_execz .LBB0_172
	v_lshl_add_u64 v[6:7], s[6:7], 0, v[2:3]
	v_lshl_add_u64 v[6:7], v[4:5], 1, v[6:7]
	global_load_dwordx4 v[6:9], v[6:7], off nt
	s_waitcnt vmcnt(0)
	v_lshlrev_b32_e32 v38, 16, v6
	v_lshlrev_b32_e32 v39, 16, v7
	v_and_b32_e32 v37, 0xffff0000, v7
	v_and_b32_e32 v36, 0xffff0000, v6
	v_lshlrev_b32_e32 v42, 16, v8
	v_lshlrev_b32_e32 v43, 16, v9
	v_and_b32_e32 v41, 0xffff0000, v9
	v_and_b32_e32 v40, 0xffff0000, v8
.LBB0_172:
	s_or_b64 exec, exec, s[48:49]
	v_lshl_add_u64 v[6:7], s[42:43], 0, v[2:3]
	v_lshlrev_b64 v[4:5], 1, v[4:5]
	v_lshl_add_u64 v[6:7], v[6:7], 0, v[4:5]
	global_load_dwordx4 v[6:9], v[6:7], off nt
	s_waitcnt vmcnt(6)
	v_mov_b32_e32 v34, v12
	s_waitcnt vmcnt(5)
	v_mov_b32_e32 v35, v16
	v_lshl_add_u64 v[2:3], v[2:3], 0, v[4:5]
	s_waitcnt vmcnt(2)
	v_mov_b32_e32 v44, v28
	v_mov_b32_e32 v45, v20
	s_waitcnt vmcnt(1)
	v_mov_b32_e32 v46, v32
	v_mov_b32_e32 v47, v24
	v_swap_b32 v16, v15
	v_swap_b32 v20, v19
	v_swap_b32 v24, v23
	v_swap_b32 v12, v11
	v_swap_b32 v28, v27
	v_swap_b32 v32, v31
	v_add_u32_e32 v55, 3, v1
	v_lshl_add_u64 v[34:35], s[54:55], 0, v[2:3]
	s_mov_b64 s[48:49], 0
	s_waitcnt vmcnt(0)
	v_lshlrev_b32_e32 v2, 16, v6
	v_and_b32_e32 v3, 0xffff0000, v6
	v_lshlrev_b32_e32 v4, 16, v7
	v_and_b32_e32 v5, 0xffff0000, v7
	v_lshlrev_b32_e32 v6, 16, v8
	v_and_b32_e32 v7, 0xffff0000, v8
	v_lshlrev_b32_e32 v8, 16, v9
	v_and_b32_e32 v9, 0xffff0000, v9
	s_branch .LBB0_174
.LBB0_173:
	s_or_b64 exec, exec, s[60:61]
	v_add_co_u32_e32 v56, vcc, 0x10003000, v44
	v_pk_mul_f32 v[60:61], v[18:19], v[38:39]
	s_nop 0
	v_addc_co_u32_e32 v57, vcc, 0, v45, vcc
	global_load_dwordx4 v[56:59], v[56:57], off nt
	v_pk_mul_f32 v[64:65], v[20:21], v[36:37]
	v_pk_mul_f32 v[68:69], v[26:27], v[42:43]
	v_add_co_u32_e32 v76, vcc, s66, v44
	v_mov_b32_e32 v62, v2
	v_mov_b32_e32 v63, v4
	v_mov_b32_e32 v66, v3
	v_mov_b32_e32 v67, v5
	v_mov_b32_e32 v70, v6
	v_mov_b32_e32 v71, v8
	v_pk_mul_f32 v[72:73], v[28:29], v[40:41]
	v_addc_co_u32_e32 v77, vcc, 0, v45, vcc
	v_pk_fma_f32 v[44:45], v[14:15], v[48:49], v[60:61]
	v_pk_fma_f32 v[46:47], v[16:17], v[46:47], v[64:65]
	v_pk_fma_f32 v[48:49], v[10:11], v[52:53], v[68:69]
	v_mov_b32_e32 v74, v7
	v_mov_b32_e32 v75, v9
	v_pk_fma_f32 v[50:51], v[12:13], v[50:51], v[72:73]
	v_pk_fma_f32 v[44:45], v[22:23], v[62:63], v[44:45]
	v_pk_fma_f32 v[46:47], v[24:25], v[66:67], v[46:47]
	v_pk_fma_f32 v[48:49], v[30:31], v[70:71], v[48:49]
	v_pk_fma_f32 v[50:51], v[32:33], v[74:75], v[50:51]
	s_add_u32 s48, s48, 0x4000
	s_addc_u32 s49, s49, 0
	s_cmp_eq_u32 s48, 0x10000
	v_add_u32_e32 v55, 4, v55
	s_waitcnt vmcnt(0)
	v_lshlrev_b32_e32 v53, 16, v57
	v_lshlrev_b32_e32 v52, 16, v56
	v_and_b32_e32 v57, 0xffff0000, v57
	v_and_b32_e32 v56, 0xffff0000, v56
	v_lshlrev_b32_e32 v61, 16, v59
	v_lshlrev_b32_e32 v60, 16, v58
	v_and_b32_e32 v59, 0xffff0000, v59
	v_and_b32_e32 v58, 0xffff0000, v58
	v_pk_mul_f32 v[44:45], v[44:45], v[52:53]
	v_pk_mul_f32 v[46:47], v[46:47], v[56:57]
	v_pk_mul_f32 v[48:49], v[48:49], v[60:61]
	v_pk_mul_f32 v[50:51], v[50:51], v[58:59]
	v_bfe_u32 v53, v47, 16, 1
	v_bfe_u32 v57, v44, 16, 1
	v_bfe_u32 v58, v45, 16, 1
	v_bfe_u32 v59, v48, 16, 1
	v_bfe_u32 v60, v49, 16, 1
	v_bfe_u32 v1, v51, 16, 1
	v_bfe_u32 v52, v50, 16, 1
	v_bfe_u32 v56, v46, 16, 1
	v_add3_u32 v53, v47, v53, s25
	v_add3_u32 v47, v49, v60, s25
	v_add3_u32 v48, v48, v59, s25
	v_add3_u32 v45, v45, v58, s25
	v_add3_u32 v44, v44, v57, s25
	v_add3_u32 v56, v46, v56, s25
	v_add3_u32 v46, v50, v52, s25
	v_add3_u32 v1, v51, v1, s25
	v_lshrrev_b32_e32 v44, 16, v44
	v_lshrrev_b32_e32 v45, 16, v45
	v_lshrrev_b32_e32 v48, 16, v48
	v_lshrrev_b32_e32 v47, 16, v47
	v_and_or_b32 v47, v1, s24, v47
	v_and_or_b32 v46, v46, s24, v48
	v_and_or_b32 v45, v53, s24, v45
	v_and_or_b32 v44, v56, s24, v44
	global_store_dwordx4 v[76:77], v[44:47], off
	s_cbranch_scc1 .LBB0_169
; __device__ __forceinline__ unsigned pk2(float lo, float hi) { return f2bf(lo) | (f2bf(hi) << 16); }
; __device__ __forceinline__ void load_cu(const bf16* bcu, size_t tok, int col, float (&cu)[8]) {
;     const v4u c = *(const v4u*)(bcu + (size_t)M * D + tok * (size_t)D + col);
;     cu[0] = bflo(c.x); cu[1] = bfhi(c.x); cu[2] = bflo(c.y); cu[3] = bfhi(c.y); cu[4] = bflo(c.z); cu[5] = bfhi(c.z); cu[6] = bflo(c.w); cu[7] = bfhi(c.w);
; __device__ __forceinline__ void conv_phase(const bf16* bcu, const float* cw, bf16* Y, int gtid, int gthreads) {
;     ...
;         for (int i = 0; i < CH; ++i) {
;             const size_t t = t0 + i;
;             if (s0 + i + 1 < SEQ) load_cu(bcu, t + 1, col, nxt); else {
; #pragma unroll
;                 for (int e = 0; e < 8; ++e) nxt[e] = 0.f; }
;             const v4u bb = *(const v4u*)(bcu + t * (size_t)D + col);
;             float g[8] = {bflo(bb.x), bfhi(bb.x), bflo(bb.y), bfhi(bb.y), bflo(bb.z), bfhi(bb.z), bflo(bb.w), bfhi(bb.w)};
;             float y[8];
; #pragma unroll
;             for (int e = 0; e < 8; ++e) { y[e] = g[e] * (w0[e] * prev[e] + w1[e] * cur[e] + w2[e] * nxt[e]); prev[e] = cur[e]; cur[e] = nxt[e]; }
;             v4u o; o.x = pk2(y[0], y[1]); o.y = pk2(y[2], y[3]); o.z = pk2(y[4], y[5]); o.w = pk2(y[6], y[7]);
;             *(v4u*)(Y + t * (size_t)D + col) = o;
.LBB0_174:
	s_nop 0
	v_lshl_add_u64 v[44:45], v[34:35], 0, s[48:49]
	v_add_co_u32_e32 v56, vcc, s33, v44
	v_mov_b32_e32 v72, v2
	s_nop 0
	v_addc_co_u32_e32 v57, vcc, 0, v45, vcc
	global_load_dwordx4 v[46:49], v[56:57], off offset:-4096 nt
	v_add_co_u32_e32 v60, vcc, s35, v44
	v_mov_b32_e32 v73, v4
	s_nop 0
	v_addc_co_u32_e32 v61, vcc, 0, v45, vcc
	global_load_dwordx4 v[50:53], v[60:61], off offset:-4096 nt
	s_nop 0
	global_load_dwordx4 v[56:59], v[56:57], off nt
	v_add_co_u32_e32 v70, vcc, s63, v44
	global_load_dwordx4 v[60:63], v[60:61], off nt
	v_mov_b32_e32 v4, v3
	v_mov_b32_e32 v2, v6
	v_mov_b32_e32 v3, v8
	v_mov_b32_e32 v8, v7
	v_addc_co_u32_e32 v71, vcc, 0, v45, vcc
	v_pk_mul_f32 v[6:7], v[18:19], v[72:73]
	v_pk_mul_f32 v[64:65], v[20:21], v[4:5]
	v_pk_mul_f32 v[66:67], v[26:27], v[2:3]
	v_pk_mul_f32 v[68:69], v[28:29], v[8:9]
	v_add_co_u32_e32 v74, vcc, s64, v44
	v_pk_fma_f32 v[6:7], v[14:15], v[38:39], v[6:7]
	s_nop 0
	v_addc_co_u32_e32 v75, vcc, 0, v45, vcc
	v_pk_fma_f32 v[36:37], v[16:17], v[36:37], v[64:65]
	v_pk_fma_f32 v[38:39], v[10:11], v[42:43], v[66:67]
	v_pk_fma_f32 v[40:41], v[12:13], v[40:41], v[68:69]
	global_load_dwordx4 v[64:67], v[70:71], off nt
	s_nop 0
	global_load_dwordx4 v[68:71], v[74:75], off nt
	s_waitcnt vmcnt(5)
	v_lshlrev_b32_e32 v74, 16, v46
	v_lshlrev_b32_e32 v75, 16, v47
	v_lshlrev_b32_e32 v78, 16, v48
	v_lshlrev_b32_e32 v79, 16, v49
	v_and_b32_e32 v76, 0xffff0000, v46
	v_and_b32_e32 v77, 0xffff0000, v47
	v_and_b32_e32 v80, 0xffff0000, v48
	v_and_b32_e32 v81, 0xffff0000, v49
	s_waitcnt vmcnt(4)
	v_lshlrev_b32_e32 v43, 16, v51
	v_lshlrev_b32_e32 v42, 16, v50
	v_pk_fma_f32 v[6:7], v[22:23], v[74:75], v[6:7]
	v_lshlrev_b32_e32 v49, 16, v53
	v_lshlrev_b32_e32 v48, 16, v52
	v_pk_fma_f32 v[38:39], v[30:31], v[78:79], v[38:39]
	v_and_b32_e32 v47, 0xffff0000, v51
	v_and_b32_e32 v46, 0xffff0000, v50
	v_pk_fma_f32 v[36:37], v[24:25], v[76:77], v[36:37]
	v_and_b32_e32 v51, 0xffff0000, v53
	v_and_b32_e32 v50, 0xffff0000, v52
	v_pk_fma_f32 v[40:41], v[32:33], v[80:81], v[40:41]
	v_pk_mul_f32 v[6:7], v[6:7], v[42:43]
	v_pk_mul_f32 v[38:39], v[38:39], v[48:49]
	v_pk_mul_f32 v[36:37], v[36:37], v[46:47]
	v_pk_mul_f32 v[40:41], v[40:41], v[50:51]
	v_bfe_u32 v47, v6, 16, 1
	v_bfe_u32 v49, v38, 16, 1
	v_bfe_u32 v42, v40, 16, 1
	v_bfe_u32 v46, v36, 16, 1
	v_bfe_u32 v48, v7, 16, 1
	v_bfe_u32 v50, v39, 16, 1
	v_add3_u32 v38, v38, v49, s25
	v_add3_u32 v6, v6, v47, s25
	v_bfe_u32 v1, v41, 16, 1
	v_bfe_u32 v43, v37, 16, 1
	v_add3_u32 v36, v36, v46, s25
	v_add3_u32 v40, v40, v42, s25
	v_add3_u32 v39, v39, v50, s25
	v_add3_u32 v7, v7, v48, s25
	v_lshrrev_b32_e32 v6, 16, v6
	v_lshrrev_b32_e32 v38, 16, v38
	v_add3_u32 v37, v37, v43, s25
	v_add3_u32 v1, v41, v1, s25
	v_lshrrev_b32_e32 v7, 16, v7
	v_lshrrev_b32_e32 v39, 16, v39
	v_and_or_b32 v38, v40, s24, v38
	v_and_or_b32 v36, v36, s24, v6
	v_add_co_u32_e32 v6, vcc, s62, v44
	v_pk_mul_f32 v[40:41], v[18:19], v[74:75]
	v_and_or_b32 v39, v1, s24, v39
	v_and_or_b32 v37, v37, s24, v7
	v_addc_co_u32_e32 v7, vcc, 0, v45, vcc
	s_waitcnt vmcnt(3)
	v_lshlrev_b32_e32 v48, 16, v56
	v_lshlrev_b32_e32 v49, 16, v57
	v_pk_fma_f32 v[40:41], v[14:15], v[72:73], v[40:41]
	global_store_dwordx4 v[6:7], v[36:39], off offset:-4096
	v_pk_fma_f32 v[40:41], v[22:23], v[48:49], v[40:41]
	v_and_b32_e32 v46, 0xffff0000, v56
	s_waitcnt vmcnt(3)
; __device__ __forceinline__ unsigned pk2(float lo, float hi) { return f2bf(lo) | (f2bf(hi) << 16); }
; __device__ __forceinline__ void load_cu(const bf16* bcu, size_t tok, int col, float (&cu)[8]) {
;     const v4u c = *(const v4u*)(bcu + (size_t)M * D + tok * (size_t)D + col);
;     cu[0] = bflo(c.x); cu[1] = bfhi(c.x); cu[2] = bflo(c.y); cu[3] = bfhi(c.y); cu[4] = bflo(c.z); cu[5] = bfhi(c.z); cu[6] = bflo(c.w); cu[7] = bfhi(c.w);
; __device__ __forceinline__ void conv_phase(const bf16* bcu, const float* cw, bf16* Y, int gtid, int gthreads) {
;     ...
;         for (int i = 0; i < CH; ++i) {
;             const size_t t = t0 + i;
;             if (s0 + i + 1 < SEQ) load_cu(bcu, t + 1, col, nxt); else {
; #pragma unroll
;                 for (int e = 0; e < 8; ++e) nxt[e] = 0.f; }
;             const v4u bb = *(const v4u*)(bcu + t * (size_t)D + col);
;             float g[8] = {bflo(bb.x), bfhi(bb.x), bflo(bb.y), bfhi(bb.y), bflo(bb.z), bfhi(bb.z), bflo(bb.w), bfhi(bb.w)};
;             float y[8];
; #pragma unroll
;             for (int e = 0; e < 8; ++e) { y[e] = g[e] * (w0[e] * prev[e] + w1[e] * cur[e] + w2[e] * nxt[e]); prev[e] = cur[e]; cur[e] = nxt[e]; }
;             v4u o; o.x = pk2(y[0], y[1]); o.y = pk2(y[2], y[3]); o.z = pk2(y[4], y[5]); o.w = pk2(y[6], y[7]);
;             *(v4u*)(Y + t * (size_t)D + col) = o;
	v_lshlrev_b32_e32 v37, 16, v61
	v_lshlrev_b32_e32 v36, 16, v60
	v_pk_mul_f32 v[36:37], v[40:41], v[36:37]
	v_pk_mul_f32 v[40:41], v[20:21], v[76:77]
	v_and_b32_e32 v47, 0xffff0000, v57
	v_pk_fma_f32 v[4:5], v[16:17], v[4:5], v[40:41]
	v_pk_mul_f32 v[42:43], v[26:27], v[78:79]
	v_lshlrev_b32_e32 v52, 16, v58
	v_lshlrev_b32_e32 v53, 16, v59
	v_and_b32_e32 v39, 0xffff0000, v61
	v_and_b32_e32 v38, 0xffff0000, v60
	v_pk_fma_f32 v[4:5], v[24:25], v[46:47], v[4:5]
	v_pk_fma_f32 v[2:3], v[10:11], v[2:3], v[42:43]
	v_pk_mul_f32 v[4:5], v[4:5], v[38:39]
	v_lshlrev_b32_e32 v39, 16, v63
	v_lshlrev_b32_e32 v38, 16, v62
	v_pk_fma_f32 v[2:3], v[30:31], v[52:53], v[2:3]
	v_and_b32_e32 v50, 0xffff0000, v58
	v_pk_mul_f32 v[2:3], v[2:3], v[38:39]
	v_pk_mul_f32 v[38:39], v[28:29], v[80:81]
	v_and_b32_e32 v51, 0xffff0000, v59
	v_pk_fma_f32 v[8:9], v[12:13], v[8:9], v[38:39]
	v_and_b32_e32 v41, 0xffff0000, v63
	v_and_b32_e32 v40, 0xffff0000, v62
	v_pk_fma_f32 v[8:9], v[32:33], v[50:51], v[8:9]
	v_bfe_u32 v39, v5, 16, 1
	v_pk_mul_f32 v[8:9], v[8:9], v[40:41]
	v_bfe_u32 v40, v4, 16, 1
	v_bfe_u32 v1, v9, 16, 1
	v_bfe_u32 v38, v8, 16, 1
	v_add3_u32 v40, v4, v40, s25
	v_add3_u32 v39, v5, v39, s25
	v_add3_u32 v4, v8, v38, s25
	v_add3_u32 v1, v9, v1, s25
	v_bfe_u32 v5, v36, 16, 1
	v_bfe_u32 v8, v37, 16, 1
	v_bfe_u32 v9, v2, 16, 1
	v_bfe_u32 v38, v3, 16, 1
	v_add3_u32 v3, v3, v38, s25
	v_add3_u32 v2, v2, v9, s25
	v_add3_u32 v8, v37, v8, s25
	v_add3_u32 v5, v36, v5, s25
	v_lshrrev_b32_e32 v9, 16, v5
	v_lshrrev_b32_e32 v8, 16, v8
	v_lshrrev_b32_e32 v2, 16, v2
	v_lshrrev_b32_e32 v3, 16, v3
	v_and_or_b32 v5, v1, s24, v3
	v_and_or_b32 v4, v4, s24, v2
	v_and_or_b32 v3, v39, s24, v8
	v_and_or_b32 v2, v40, s24, v9
	global_store_dwordx4 v[6:7], v[2:5], off
	v_pk_mul_f32 v[6:7], v[18:19], v[48:49]
	s_waitcnt vmcnt(3)
	v_lshlrev_b32_e32 v38, 16, v64
	v_lshlrev_b32_e32 v39, 16, v65
	v_pk_fma_f32 v[6:7], v[14:15], v[74:75], v[6:7]
	s_waitcnt vmcnt(2)
	v_lshlrev_b32_e32 v3, 16, v69
	v_lshlrev_b32_e32 v2, 16, v68
	v_pk_fma_f32 v[6:7], v[22:23], v[38:39], v[6:7]
	v_and_b32_e32 v36, 0xffff0000, v64
	v_pk_mul_f32 v[2:3], v[6:7], v[2:3]
	v_pk_mul_f32 v[6:7], v[20:21], v[46:47]
	v_and_b32_e32 v37, 0xffff0000, v65
	v_pk_fma_f32 v[6:7], v[16:17], v[76:77], v[6:7]
	v_pk_mul_f32 v[56:57], v[26:27], v[52:53]
	v_lshlrev_b32_e32 v42, 16, v66
	v_lshlrev_b32_e32 v43, 16, v67
	v_and_b32_e32 v5, 0xffff0000, v69
	v_and_b32_e32 v4, 0xffff0000, v68
	v_pk_fma_f32 v[6:7], v[24:25], v[36:37], v[6:7]
	v_pk_fma_f32 v[56:57], v[10:11], v[78:79], v[56:57]
	v_pk_mul_f32 v[4:5], v[6:7], v[4:5]
	v_lshlrev_b32_e32 v7, 16, v71
	v_lshlrev_b32_e32 v6, 16, v70
	v_pk_fma_f32 v[56:57], v[30:31], v[42:43], v[56:57]
	v_and_b32_e32 v40, 0xffff0000, v66
	v_pk_mul_f32 v[6:7], v[56:57], v[6:7]
	v_pk_mul_f32 v[56:57], v[28:29], v[50:51]
	v_and_b32_e32 v41, 0xffff0000, v67
	v_pk_fma_f32 v[56:57], v[12:13], v[80:81], v[56:57]
	v_and_b32_e32 v9, 0xffff0000, v71
	v_and_b32_e32 v8, 0xffff0000, v70
	v_pk_fma_f32 v[56:57], v[32:33], v[40:41], v[56:57]
	v_bfe_u32 v58, v4, 16, 1
	v_pk_mul_f32 v[8:9], v[56:57], v[8:9]
	v_bfe_u32 v57, v5, 16, 1
	v_bfe_u32 v1, v9, 16, 1
	v_bfe_u32 v56, v8, 16, 1
	v_add3_u32 v1, v9, v1, s25
	v_bfe_u32 v9, v6, 16, 1
	v_add3_u32 v58, v4, v58, s25
	v_add3_u32 v57, v5, v57, s25
	v_add3_u32 v4, v8, v56, s25
	v_bfe_u32 v5, v2, 16, 1
	v_bfe_u32 v8, v3, 16, 1
	v_bfe_u32 v56, v7, 16, 1
	v_add3_u32 v6, v6, v9, s25
	v_add3_u32 v7, v7, v56, s25
	v_add3_u32 v3, v3, v8, s25
	v_add3_u32 v2, v2, v5, s25
	v_lshrrev_b32_e32 v6, 16, v6
	v_lshrrev_b32_e32 v2, 16, v2
	v_lshrrev_b32_e32 v3, 16, v3
	v_lshrrev_b32_e32 v5, 16, v7
	v_and_or_b32 v4, v4, s24, v6
	v_add_co_u32_e32 v6, vcc, 0xc002000, v44
	v_and_or_b32 v5, v1, s24, v5
	v_and_or_b32 v3, v57, s24, v3
	v_and_or_b32 v2, v58, s24, v2
	v_addc_co_u32_e32 v7, vcc, 0, v45, vcc
	global_store_dwordx4 v[6:7], v[2:5], off
	v_mov_b32_e32 v6, v0
	v_mov_b32_e32 v7, v0
	v_mov_b32_e32 v2, v0
	v_mov_b32_e32 v3, v0
	v_mov_b32_e32 v4, v0
	v_mov_b32_e32 v5, v0
	v_mov_b32_e32 v1, v0
	v_mov_b64_e32 v[8:9], v[6:7]
	v_cmp_gt_u32_e32 vcc, s65, v55
	v_mov_b64_e32 v[6:7], v[4:5]
	v_mov_b64_e32 v[4:5], v[2:3]
	v_mov_b64_e32 v[2:3], v[0:1]
	s_and_saveexec_b64 s[60:61], vcc
	s_cbranch_execz .LBB0_173
	v_add_co_u32_e32 v2, vcc, 0x14004000, v44
	s_nop 1
	v_addc_co_u32_e32 v3, vcc, 0, v45, vcc
	global_load_dwordx4 v[6:9], v[2:3], off nt
	s_waitcnt vmcnt(0)
	v_lshlrev_b32_e32 v2, 16, v6
	v_and_b32_e32 v3, 0xffff0000, v6
	v_lshlrev_b32_e32 v4, 16, v7
	v_and_b32_e32 v5, 0xffff0000, v7
	v_lshlrev_b32_e32 v6, 16, v8
	v_and_b32_e32 v7, 0xffff0000, v8
	v_lshlrev_b32_e32 v8, 16, v9
	v_and_b32_e32 v9, 0xffff0000, v9
	s_branch .LBB0_173

; __device__ __forceinline__ unsigned cvt_pk_bf16(float lo, float hi) { unsigned r; asm volatile("v_cvt_pk_bf16_f32 %0, %1, %2" : "=v"(r) : "v"(lo), "v"(hi)); return r; }
;     __device__ __forceinline__ void operator()(const f32x4 (&acc)[2][2][4][2], const Unit& u, int wr, int wc, int fr, int fq) const {
;     ...
;         if (F32BASE) {
; #pragma unroll
;             for (int ai = 0; ai < 2; ++ai)
; #pragma unroll
;                 for (int m = 0; m < 4; ++m) { const size_t roff = (size_t)(row0 + ai * HALF + m * 16) * ldc + col0;
; #pragma unroll
;                     for (int bj = 0; bj < 2; ++bj) { const size_t off = roff + bj * HALF; const f32x4 v0 = acc[ai][bj][m][0] + *(const f32x4*)(basef + off), v1 = acc[ai][bj][m][1] + *(const f32x4*)(basef + off + 4);
;                         u32x4 w; w.x = cvt_pk_bf16(v0[0], v0[1]); w.y = cvt_pk_bf16(v0[2], v0[3]); w.z = cvt_pk_bf16(v1[0], v1[1]); w.w = cvt_pk_bf16(v1[2], v1[3]);
;                         *(u32x4*)(outb + off) = w; }
;                     if (m & 1) asm volatile("" ::: "memory"); }
.LBB0_248:
	v_lshl_add_u32 v148, s68, 8, v150
	v_lshl_or_b32 v146, s24, 8, v152
	v_ashrrev_i32_e32 v149, 31, v148
	v_ashrrev_i32_e32 v147, 31, v146
	v_lshlrev_b64 v[144:145], 11, v[148:149]
	v_lshl_add_u64 v[144:145], v[144:145], 0, v[146:147]
	v_lshl_add_u64 v[164:165], v[144:145], 2, s[36:37]
	global_load_dwordx4 v[156:159], v[164:165], off nt
	global_load_dwordx4 v[160:163], v[164:165], off offset:16 nt
	v_lshl_add_u64 v[166:167], v[144:145], 1, s[52:53]
	s_mov_b64 s[24:25], 0x40000
	s_andn2_b64 vcc, exec, s[4:5]
	s_mov_b64 s[4:5], -1
	s_waitcnt vmcnt(0)
	v_pk_add_f32 v[124:125], v[124:125], v[156:157]
	v_pk_add_f32 v[156:157], v[122:123], v[162:163]
	v_pk_add_f32 v[122:123], v[120:121], v[160:161]
	v_pk_add_f32 v[126:127], v[126:127], v[158:159]
	v_cvt_pk_bf16_f32 v120, v124, v125
	s_nop 0
	v_cvt_pk_bf16_f32 v121, v126, v127
	v_cvt_pk_bf16_f32 v122, v122, v123
	v_cvt_pk_bf16_f32 v123, v156, v157
	global_store_dwordx4 v[166:167], v[120:123], off
	global_load_dwordx4 v[120:123], v[164:165], off offset:512 nt
	s_nop 0
	global_load_dwordx4 v[124:127], v[164:165], off offset:528 nt
	v_or_b32_e32 v156, 16, v148
	v_ashrrev_i32_e32 v157, 31, v156
	v_lshlrev_b64 v[156:157], 11, v[156:157]
	v_lshl_add_u64 v[156:157], v[156:157], 0, v[146:147]
	v_lshl_add_u64 v[158:159], v[156:157], 2, s[36:37]
	s_waitcnt vmcnt(1)
	v_pk_add_f32 v[116:117], v[116:117], v[120:121]
	s_waitcnt vmcnt(0)
	v_pk_add_f32 v[120:121], v[114:115], v[126:127]
	v_pk_add_f32 v[114:115], v[112:113], v[124:125]
	v_pk_add_f32 v[118:119], v[118:119], v[122:123]
	v_cvt_pk_bf16_f32 v112, v116, v117
	s_nop 0
	v_cvt_pk_bf16_f32 v113, v118, v119
	v_cvt_pk_bf16_f32 v114, v114, v115
	v_cvt_pk_bf16_f32 v115, v120, v121
	global_store_dwordx4 v[166:167], v[112:115], off offset:256
	global_load_dwordx4 v[112:115], v[158:159], off nt
	s_nop 0
	global_load_dwordx4 v[116:119], v[158:159], off offset:16 nt
	v_lshl_add_u64 v[120:121], v[156:157], 1, s[52:53]
	s_waitcnt vmcnt(1)
	v_pk_add_f32 v[108:109], v[108:109], v[112:113]
	s_waitcnt vmcnt(0)
	v_pk_add_f32 v[112:113], v[106:107], v[118:119]
	v_pk_add_f32 v[106:107], v[104:105], v[116:117]
	v_pk_add_f32 v[110:111], v[110:111], v[114:115]
	v_cvt_pk_bf16_f32 v104, v108, v109
	s_nop 0
	v_cvt_pk_bf16_f32 v105, v110, v111
	v_cvt_pk_bf16_f32 v106, v106, v107
	v_cvt_pk_bf16_f32 v107, v112, v113
	global_store_dwordx4 v[120:121], v[104:107], off
	global_load_dwordx4 v[104:107], v[158:159], off offset:512 nt
	s_nop 0
	global_load_dwordx4 v[108:111], v[158:159], off offset:528 nt
	v_or_b32_e32 v112, 32, v148
	v_ashrrev_i32_e32 v113, 31, v112
	v_lshlrev_b64 v[112:113], 11, v[112:113]
	v_lshl_add_u64 v[112:113], v[112:113], 0, v[146:147]
	v_lshl_add_u64 v[114:115], v[112:113], 2, s[36:37]
	s_waitcnt vmcnt(1)
	v_pk_add_f32 v[100:101], v[100:101], v[104:105]
	s_waitcnt vmcnt(0)
	v_pk_add_f32 v[104:105], v[98:99], v[110:111]
	v_pk_add_f32 v[98:99], v[96:97], v[108:109]
	v_pk_add_f32 v[102:103], v[102:103], v[106:107]
	v_cvt_pk_bf16_f32 v96, v100, v101
	s_nop 0
	v_cvt_pk_bf16_f32 v97, v102, v103
	v_cvt_pk_bf16_f32 v98, v98, v99
	v_cvt_pk_bf16_f32 v99, v104, v105
	global_store_dwordx4 v[120:121], v[96:99], off offset:256
	global_load_dwordx4 v[96:99], v[114:115], off nt
	global_load_dwordx4 v[100:103], v[114:115], off offset:16 nt
	v_lshl_add_u64 v[104:105], v[112:113], 1, s[52:53]
	s_waitcnt vmcnt(1)
	v_pk_add_f32 v[92:93], v[92:93], v[96:97]
	s_waitcnt vmcnt(0)
	v_pk_add_f32 v[96:97], v[90:91], v[102:103]
	v_pk_add_f32 v[90:91], v[88:89], v[100:101]
	v_pk_add_f32 v[94:95], v[94:95], v[98:99]
	v_cvt_pk_bf16_f32 v88, v92, v93
	s_nop 0
	v_cvt_pk_bf16_f32 v89, v94, v95
	v_cvt_pk_bf16_f32 v90, v90, v91
	v_cvt_pk_bf16_f32 v91, v96, v97
	global_store_dwordx4 v[104:105], v[88:91], off
	global_load_dwordx4 v[88:91], v[114:115], off offset:512 nt
	s_nop 0
	global_load_dwordx4 v[92:95], v[114:115], off offset:528 nt
	v_or_b32_e32 v96, 48, v148
	v_ashrrev_i32_e32 v97, 31, v96
	v_lshlrev_b64 v[96:97], 11, v[96:97]
	v_lshl_add_u64 v[96:97], v[96:97], 0, v[146:147]
	v_lshl_add_u64 v[98:99], v[96:97], 2, s[36:37]
	s_waitcnt vmcnt(1)
	v_pk_add_f32 v[84:85], v[84:85], v[88:89]
	s_waitcnt vmcnt(0)
	v_pk_add_f32 v[88:89], v[82:83], v[94:95]
	v_pk_add_f32 v[82:83], v[80:81], v[92:93]
	v_pk_add_f32 v[86:87], v[86:87], v[90:91]
	v_cvt_pk_bf16_f32 v80, v84, v85
	s_nop 0
	v_cvt_pk_bf16_f32 v81, v86, v87
	v_cvt_pk_bf16_f32 v82, v82, v83
	v_cvt_pk_bf16_f32 v83, v88, v89
	global_store_dwordx4 v[104:105], v[80:83], off offset:256
	global_load_dwordx4 v[80:83], v[98:99], off nt
	s_nop 0
	global_load_dwordx4 v[84:87], v[98:99], off offset:16 nt
	v_lshl_add_u64 v[88:89], v[96:97], 1, s[52:53]
	s_waitcnt vmcnt(1)
	v_pk_add_f32 v[76:77], v[76:77], v[80:81]
	s_waitcnt vmcnt(0)
	v_pk_add_f32 v[80:81], v[74:75], v[86:87]
	v_pk_add_f32 v[74:75], v[72:73], v[84:85]
	v_pk_add_f32 v[78:79], v[78:79], v[82:83]
	v_cvt_pk_bf16_f32 v72, v76, v77
	s_nop 0
	v_cvt_pk_bf16_f32 v73, v78, v79
	v_cvt_pk_bf16_f32 v74, v74, v75
	v_cvt_pk_bf16_f32 v75, v80, v81
	global_store_dwordx4 v[88:89], v[72:75], off
	global_load_dwordx4 v[72:75], v[98:99], off offset:512 nt
	s_nop 0
	global_load_dwordx4 v[76:79], v[98:99], off offset:528 nt
	v_lshl_add_u64 v[80:81], v[144:145], 0, s[24:25]
	v_lshl_add_u64 v[82:83], v[80:81], 2, s[36:37]
	s_mov_b64 s[24:25], 0x48000
	s_waitcnt vmcnt(1)
; __device__ __forceinline__ unsigned cvt_pk_bf16(float lo, float hi) { unsigned r; asm volatile("v_cvt_pk_bf16_f32 %0, %1, %2" : "=v"(r) : "v"(lo), "v"(hi)); return r; }
; #define PG8_BAR __builtin_amdgcn_s_barrier()
;     __device__ __forceinline__ void operator()(const f32x4 (&acc)[2][2][4][2], const Unit& u, int wr, int wc, int fr, int fq) const {
;     ...
;         if (F32BASE) {
; #pragma unroll
;             for (int ai = 0; ai < 2; ++ai)
; #pragma unroll
;                 for (int m = 0; m < 4; ++m) { const size_t roff = (size_t)(row0 + ai * HALF + m * 16) * ldc + col0;
; #pragma unroll
;                     for (int bj = 0; bj < 2; ++bj) { const size_t off = roff + bj * HALF; const f32x4 v0 = acc[ai][bj][m][0] + *(const f32x4*)(basef + off), v1 = acc[ai][bj][m][1] + *(const f32x4*)(basef + off + 4);
;                         u32x4 w; w.x = cvt_pk_bf16(v0[0], v0[1]); w.y = cvt_pk_bf16(v0[2], v0[3]); w.z = cvt_pk_bf16(v1[0], v1[1]); w.w = cvt_pk_bf16(v1[2], v1[3]);
;                         *(u32x4*)(outb + off) = w; }
;                     if (m & 1) asm volatile("" ::: "memory"); }
; template <class Epi, class Sched, bool ALIGN_EPI = false, bool SP2 = false>
; __device__ __forceinline__ void gemm_phase(PG8_LAS unsigned char* lds, const Gemm g, const Sched& S, const Epi& E) {
;     ...
;         if constexpr (ALIGN_EPI) { if (wr == 0) PG8_BAR; }
;         if constexpr (!Epi::AFTER_DRAIN) { E(acc, cur, wr, wc, fr, fq); S.done(cur); }
;         if (!has_next) break;
; #pragma unroll
;         for (int a = 0; a < 2; ++a)
; #pragma unroll
;             for (int b = 0; b < 2; ++b)
; #pragma unroll
;                 for (int m = 0; m < 4; ++m)
; #pragma unroll
;                     for (int n = 0; n < 2; ++n) acc[a][b][m][n] = (f32x4){0.f, 0.f, 0.f, 0.f};
;         cur = nxt; cA = nA; cB = nB; ++ui;
;         if constexpr (ALIGN_EPI) { if (wr == 1) PG8_BAR; }
	v_pk_add_f32 v[68:69], v[68:69], v[72:73]
	s_waitcnt vmcnt(0)
	v_pk_add_f32 v[72:73], v[66:67], v[78:79]
	v_pk_add_f32 v[66:67], v[64:65], v[76:77]
	v_pk_add_f32 v[70:71], v[70:71], v[74:75]
	v_cvt_pk_bf16_f32 v64, v68, v69
	s_nop 0
	v_cvt_pk_bf16_f32 v65, v70, v71
	v_cvt_pk_bf16_f32 v66, v66, v67
	v_cvt_pk_bf16_f32 v67, v72, v73
	global_store_dwordx4 v[88:89], v[64:67], off offset:256
	global_load_dwordx4 v[64:67], v[82:83], off nt
	global_load_dwordx4 v[68:71], v[82:83], off offset:16 nt
	v_lshl_add_u64 v[72:73], v[80:81], 1, s[52:53]
	s_waitcnt vmcnt(1)
	v_pk_add_f32 v[60:61], v[60:61], v[64:65]
	s_waitcnt vmcnt(0)
	v_pk_add_f32 v[64:65], v[58:59], v[70:71]
	v_pk_add_f32 v[58:59], v[56:57], v[68:69]
	v_pk_add_f32 v[62:63], v[62:63], v[66:67]
	v_cvt_pk_bf16_f32 v56, v60, v61
	s_nop 0
	v_cvt_pk_bf16_f32 v57, v62, v63
	v_cvt_pk_bf16_f32 v58, v58, v59
	v_cvt_pk_bf16_f32 v59, v64, v65
	global_store_dwordx4 v[72:73], v[56:59], off
	global_load_dwordx4 v[56:59], v[82:83], off offset:512 nt
	s_nop 0
	global_load_dwordx4 v[60:63], v[82:83], off offset:528 nt
	v_lshl_add_u64 v[64:65], v[144:145], 0, s[24:25]
	v_lshl_add_u64 v[66:67], v[64:65], 2, s[36:37]
	s_waitcnt vmcnt(1)
	v_pk_add_f32 v[52:53], v[52:53], v[56:57]
	s_waitcnt vmcnt(0)
	v_pk_add_f32 v[56:57], v[50:51], v[62:63]
	v_pk_add_f32 v[50:51], v[48:49], v[60:61]
	v_pk_add_f32 v[54:55], v[54:55], v[58:59]
	v_cvt_pk_bf16_f32 v48, v52, v53
	s_nop 0
	v_cvt_pk_bf16_f32 v49, v54, v55
	v_cvt_pk_bf16_f32 v50, v50, v51
	v_cvt_pk_bf16_f32 v51, v56, v57
	global_store_dwordx4 v[72:73], v[48:51], off offset:256
	global_load_dwordx4 v[48:51], v[66:67], off nt
	s_nop 0
	global_load_dwordx4 v[52:55], v[66:67], off offset:16 nt
	v_lshl_add_u64 v[56:57], v[64:65], 1, s[52:53]
	s_waitcnt vmcnt(1)
	v_pk_add_f32 v[44:45], v[44:45], v[48:49]
	s_waitcnt vmcnt(0)
	v_pk_add_f32 v[48:49], v[42:43], v[54:55]
	v_pk_add_f32 v[42:43], v[40:41], v[52:53]
	v_pk_add_f32 v[46:47], v[46:47], v[50:51]
	v_cvt_pk_bf16_f32 v40, v44, v45
	s_nop 0
	v_cvt_pk_bf16_f32 v41, v46, v47
	v_cvt_pk_bf16_f32 v42, v42, v43
	v_cvt_pk_bf16_f32 v43, v48, v49
	global_store_dwordx4 v[56:57], v[40:43], off
	global_load_dwordx4 v[40:43], v[66:67], off offset:512 nt
	s_nop 0
	global_load_dwordx4 v[44:47], v[66:67], off offset:528 nt
	v_lshl_add_u64 v[48:49], v[144:145], 0, s[44:45]
	v_lshl_add_u64 v[50:51], v[48:49], 2, s[36:37]
	s_waitcnt vmcnt(1)
	v_pk_add_f32 v[36:37], v[36:37], v[40:41]
	s_waitcnt vmcnt(0)
	v_pk_add_f32 v[40:41], v[34:35], v[46:47]
	v_pk_add_f32 v[34:35], v[32:33], v[44:45]
	v_pk_add_f32 v[38:39], v[38:39], v[42:43]
	v_cvt_pk_bf16_f32 v32, v36, v37
	s_nop 0
	v_cvt_pk_bf16_f32 v33, v38, v39
	v_cvt_pk_bf16_f32 v34, v34, v35
	v_cvt_pk_bf16_f32 v35, v40, v41
	global_store_dwordx4 v[56:57], v[32:35], off offset:256
	global_load_dwordx4 v[32:35], v[50:51], off nt
	global_load_dwordx4 v[36:39], v[50:51], off offset:16 nt
	v_lshl_add_u64 v[40:41], v[48:49], 1, s[52:53]
	s_waitcnt vmcnt(1)
	v_pk_add_f32 v[28:29], v[28:29], v[32:33]
	s_waitcnt vmcnt(0)
	v_pk_add_f32 v[32:33], v[26:27], v[38:39]
	v_pk_add_f32 v[26:27], v[24:25], v[36:37]
	v_pk_add_f32 v[30:31], v[30:31], v[34:35]
	v_cvt_pk_bf16_f32 v24, v28, v29
	s_nop 0
	v_cvt_pk_bf16_f32 v25, v30, v31
	v_cvt_pk_bf16_f32 v26, v26, v27
	v_cvt_pk_bf16_f32 v27, v32, v33
	global_store_dwordx4 v[40:41], v[24:27], off
	global_load_dwordx4 v[24:27], v[50:51], off offset:512 nt
	s_nop 0
	global_load_dwordx4 v[28:31], v[50:51], off offset:528 nt
	v_lshl_add_u64 v[32:33], v[144:145], 0, s[48:49]
	v_lshl_add_u64 v[34:35], v[32:33], 2, s[36:37]
	s_waitcnt vmcnt(1)
	v_pk_add_f32 v[20:21], v[20:21], v[24:25]
	s_waitcnt vmcnt(0)
	v_pk_add_f32 v[24:25], v[18:19], v[30:31]
	v_pk_add_f32 v[18:19], v[16:17], v[28:29]
	v_pk_add_f32 v[22:23], v[22:23], v[26:27]
	v_cvt_pk_bf16_f32 v16, v20, v21
	s_nop 0
	v_cvt_pk_bf16_f32 v17, v22, v23
	v_cvt_pk_bf16_f32 v18, v18, v19
	v_cvt_pk_bf16_f32 v19, v24, v25
	global_store_dwordx4 v[40:41], v[16:19], off offset:256
	global_load_dwordx4 v[16:19], v[34:35], off nt
	s_nop 0
	global_load_dwordx4 v[20:23], v[34:35], off offset:16 nt
	v_lshl_add_u64 v[24:25], v[32:33], 1, s[52:53]
	s_waitcnt vmcnt(1)
	v_pk_add_f32 v[12:13], v[12:13], v[16:17]
	s_waitcnt vmcnt(0)
	v_pk_add_f32 v[16:17], v[10:11], v[22:23]
	v_pk_add_f32 v[10:11], v[8:9], v[20:21]
	v_pk_add_f32 v[14:15], v[14:15], v[18:19]
	v_cvt_pk_bf16_f32 v8, v12, v13
	s_nop 0
	v_cvt_pk_bf16_f32 v9, v14, v15
	v_cvt_pk_bf16_f32 v10, v10, v11
	v_cvt_pk_bf16_f32 v11, v16, v17
	global_store_dwordx4 v[24:25], v[8:11], off
	global_load_dwordx4 v[8:11], v[34:35], off offset:512 nt
	s_nop 0
	global_load_dwordx4 v[12:15], v[34:35], off offset:528 nt
	s_waitcnt vmcnt(1)
	v_pk_add_f32 v[4:5], v[4:5], v[8:9]
	s_waitcnt vmcnt(0)
	v_pk_add_f32 v[8:9], v[2:3], v[14:15]
	v_pk_add_f32 v[2:3], v[0:1], v[12:13]
	v_pk_add_f32 v[6:7], v[6:7], v[10:11]
	v_cvt_pk_bf16_f32 v0, v4, v5
	s_nop 0
	v_cvt_pk_bf16_f32 v1, v6, v7
	v_cvt_pk_bf16_f32 v2, v2, v3
	v_cvt_pk_bf16_f32 v3, v8, v9
	global_store_dwordx4 v[24:25], v[0:3], off offset:256
	s_cbranch_vccnz .LBB0_237
	s_andn2_b64 vcc, exec, s[6:7]
	s_cbranch_vccnz .LBB0_236
	s_barrier
	s_branch .LBB0_236

; __device__ __forceinline__ void rms_rows2_b2f(const bf16* x0, const bf16* x1, const float* g, float* o0, float* o1, int lane) {
;     const v4u* xr0 = (const v4u*)x0 + lane; const v4u* xr1 = (const v4u*)x1 + lane; const f32x4* gr = (const f32x4*)g + 2 * lane;
;     v4u v[4], w[4]; float s = 0.f, t = 0.f;
; #pragma unroll
;     for (int j = 0; j < 4; ++j) { v[j] = xr0[64 * j]; w[j] = xr1[64 * j]; }
; #pragma unroll
;     for (int j = 0; j < 4; ++j) {
;         s += (bflo(v[j].x) * bflo(v[j].x) + bfhi(v[j].x) * bfhi(v[j].x)) + (bflo(v[j].y) * bflo(v[j].y) + bfhi(v[j].y) * bfhi(v[j].y)) + (bflo(v[j].z) * bflo(v[j].z) + bfhi(v[j].z) * bfhi(v[j].z)) + (bflo(v[j].w) * bflo(v[j].w) + bfhi(v[j].w) * bfhi(v[j].w));
;         t += (bflo(w[j].x) * bflo(w[j].x) + bfhi(w[j].x) * bfhi(w[j].x)) + (bflo(w[j].y) * bflo(w[j].y) + bfhi(w[j].y) * bfhi(w[j].y)) + (bflo(w[j].z) * bflo(w[j].z) + bfhi(w[j].z) * bfhi(w[j].z)) + (bflo(w[j].w) * bflo(w[j].w) + bfhi(w[j].w) * bfhi(w[j].w)); }
;     const float rs = 1.f / sqrtf(wave_sum(s, lane) * (1.f / D) + NORM_EPS), rt = 1.f / sqrtf(wave_sum(t, lane) * (1.f / D) + NORM_EPS);
.LBB0_1473:
	v_lshl_add_u64 v[18:19], s[14:15], 0, v[16:17]
	v_lshl_add_u64 v[20:21], s[8:9], 0, v[16:17]
	global_load_dwordx4 v[0:3], v[10:11], off offset:16
	global_load_dwordx4 v[4:7], v[10:11], off
	global_load_dwordx4 v[22:25], v[20:21], off offset:-2048 nt
	global_load_dwordx4 v[26:29], v[20:21], off offset:-1024 nt
	global_load_dwordx4 v[30:33], v[20:21], off nt
	global_load_dwordx4 v[34:37], v[20:21], off offset:1024 nt
	v_add_co_u32_e32 v18, vcc, 0xc000000, v18
	v_lshl_add_u64 v[52:53], s[12:13], 0, v[8:9]
	s_nop 0
	v_addc_co_u32_e32 v19, vcc, 0, v19, vcc
	global_load_dwordx4 v[38:41], v[18:19], off nt
	global_load_dwordx4 v[54:57], v[18:19], off offset:1024 nt
	global_load_dwordx4 v[88:91], v[18:19], off offset:2048 nt
	global_load_dwordx4 v[92:95], v[18:19], off offset:3072 nt
	v_lshl_add_u64 v[44:45], s[4:5], 0, v[8:9]
	s_add_i32 s16, s16, s34
	s_add_u32 s4, s4, s6
	s_addc_u32 s5, s5, s7
	s_add_u32 s8, s8, s10
	s_addc_u32 s9, s9, s11
	s_add_u32 s12, s12, s6
	s_addc_u32 s13, s13, s7
	s_add_u32 s14, s14, s10
	s_addc_u32 s15, s15, s11
	s_cmpk_gt_i32 s16, 0x1fff
	s_waitcnt vmcnt(7)
	v_and_b32_e32 v75, 0xffff0000, v23
	v_and_b32_e32 v47, 0xffff0000, v22
	v_and_b32_e32 v46, 0xffff0000, v24
	v_lshlrev_b32_e32 v74, 16, v23
	v_lshlrev_b32_e32 v77, 16, v22
	v_lshlrev_b32_e32 v76, 16, v24
	s_waitcnt vmcnt(6)
	v_lshlrev_b32_e32 v58, 16, v26
	v_and_b32_e32 v63, 0xffff0000, v27
	v_and_b32_e32 v62, 0xffff0000, v26
	v_lshlrev_b32_e32 v60, 16, v28
	v_and_b32_e32 v65, 0xffff0000, v29
	v_and_b32_e32 v64, 0xffff0000, v28
	s_waitcnt vmcnt(5)
	v_lshlrev_b32_e32 v48, 16, v30
	v_and_b32_e32 v49, 0xffff0000, v30
	v_lshlrev_b32_e32 v50, 16, v31
	v_and_b32_e32 v51, 0xffff0000, v31
	s_waitcnt vmcnt(4)
	v_and_b32_e32 v21, 0xffff0000, v37
	v_lshlrev_b32_e32 v26, 16, v32
	v_and_b32_e32 v23, 0xffff0000, v34
	v_and_b32_e32 v22, 0xffff0000, v32
	v_pk_mov_b32 v[30:31], v[32:33], v[36:37] op_sel:[1,0]
	v_lshlrev_b32_e32 v28, 16, v33
	v_mul_f32_e32 v20, v75, v75
	v_pk_mul_f32 v[32:33], v[46:47], v[46:47]
	v_lshlrev_b32_e32 v78, 16, v25
	v_and_b32_e32 v79, 0xffff0000, v25
	v_lshlrev_b32_e32 v59, 16, v27
	v_lshlrev_b32_e32 v61, 16, v29
	v_lshlrev_b32_e32 v18, 16, v35
	v_and_b32_e32 v19, 0xffff0000, v35
	v_lshlrev_b32_e32 v25, 16, v37
	v_lshlrev_b32_e32 v27, 16, v34
	v_lshlrev_b32_e32 v29, 16, v36
	v_pk_mul_f32 v[34:35], v[62:63], v[62:63]
	v_pk_mul_f32 v[36:37], v[64:65], v[64:65]
	v_pk_mul_f32 v[42:43], v[22:23], v[22:23]
	v_pk_fma_f32 v[102:103], v[74:75], v[74:75], v[20:21] op_sel_hi:[1,1,0]
	v_pk_fma_f32 v[104:105], v[76:77], v[76:77], v[32:33]
	v_mul_f32_e32 v24, v49, v49
	v_mul_f32_e32 v96, v51, v51
	v_mul_f32_e32 v98, v79, v79
	v_mov_b32_e32 v97, v25
	s_waitcnt vmcnt(3)
	v_and_b32_e32 v107, 0xffff0000, v39
	v_lshlrev_b32_e32 v108, 16, v40
	v_and_b32_e32 v111, 0xffff0000, v38
	v_and_b32_e32 v110, 0xffff0000, v40
	v_lshlrev_b32_e32 v112, 16, v41
	v_and_b32_e32 v113, 0xffff0000, v41
	v_pk_fma_f32 v[114:115], v[58:59], v[58:59], v[34:35]
	v_pk_fma_f32 v[116:117], v[60:61], v[60:61], v[36:37]
	s_waitcnt vmcnt(2)
	v_lshlrev_b32_e32 v67, 16, v55
	v_lshlrev_b32_e32 v66, 16, v54
	v_and_b32_e32 v71, 0xffff0000, v55
	v_and_b32_e32 v70, 0xffff0000, v54
	v_lshlrev_b32_e32 v69, 16, v57
	v_lshlrev_b32_e32 v68, 16, v56
	v_and_b32_e32 v73, 0xffff0000, v57
	v_and_b32_e32 v72, 0xffff0000, v56
	s_waitcnt vmcnt(1)
	v_lshlrev_b32_e32 v54, 16, v88
	v_and_b32_e32 v55, 0xffff0000, v88
	v_lshlrev_b32_e32 v56, 16, v89
	v_and_b32_e32 v57, 0xffff0000, v89
	v_pk_fma_f32 v[88:89], v[26:27], v[26:27], v[42:43]
	s_waitcnt vmcnt(0)
	v_lshlrev_b32_e32 v32, 16, v93
	v_and_b32_e32 v33, 0xffff0000, v93
	v_lshlrev_b32_e32 v41, 16, v92
	v_lshlrev_b32_e32 v40, 16, v90
	v_and_b32_e32 v37, 0xffff0000, v92
	v_and_b32_e32 v36, 0xffff0000, v90
	v_pk_mov_b32 v[92:93], v[90:91], v[94:95] op_sel:[1,0]
	v_lshlrev_b32_e32 v42, 16, v91
	v_pk_add_f32 v[90:91], v[104:105], v[102:103] op_sel:[1,0] op_sel_hi:[0,1]
	v_mul_f32_e32 v126, v18, v18
	v_mul_f32_e32 v127, v19, v19
	v_lshlrev_b32_e32 v106, 16, v39
	v_lshlrev_b32_e32 v109, 16, v38
	v_pk_fma_f32 v[118:119], v[48:49], v[48:49], v[24:25] op_sel_hi:[1,1,0]
	v_pk_fma_f32 v[120:121], v[50:51], v[50:51], v[96:97] op_sel_hi:[1,1,0]
	v_pk_fma_f32 v[98:99], v[78:79], v[78:79], v[98:99] op_sel_hi:[1,1,0]
	v_lshlrev_b32_e32 v39, 16, v95
	v_and_b32_e32 v35, 0xffff0000, v95
	v_lshlrev_b32_e32 v43, 16, v94
	v_mul_f32_e32 v20, v107, v107
	v_pk_mul_f32 v[94:95], v[110:111], v[110:111]
	v_pk_add_f32 v[102:103], v[114:115], v[114:115] op_sel:[0,1] op_sel_hi:[1,0]
	v_pk_add_f32 v[90:91], v[104:105], v[90:91]
	v_and_b32_e32 v31, 0xffff0000, v31
	v_and_b32_e32 v30, 0xffff0000, v30
	v_pk_mul_f32 v[114:115], v[70:71], v[70:71]
	v_mov_b32_e32 v119, v126
	v_mov_b32_e32 v121, v127
	v_mov_b32_e32 v24, v98
	v_pk_fma_f32 v[104:105], v[106:107], v[106:107], v[20:21] op_sel_hi:[1,1,0]
	v_pk_fma_f32 v[94:95], v[108:109], v[108:109], v[94:95]
	v_pk_add_f32 v[102:103], v[116:117], v[102:103]
	v_mov_b32_e32 v96, v90
	v_mul_f32_e32 v136, v21, v21
	v_mov_b32_e32 v100, v77
	v_mov_b32_e32 v101, v47
	v_pk_mul_f32 v[122:123], v[30:31], v[30:31]
	v_mov_b32_e32 v77, v46
	v_pk_mul_f32 v[124:125], v[72:73], v[72:73]
	v_pk_mul_f32 v[126:127], v[36:37], v[36:37]
	v_mul_f32_e32 v34, v55, v55
	v_mul_f32_e32 v38, v57, v57
	v_and_b32_e32 v47, 0xffff0000, v93
	v_and_b32_e32 v46, 0xffff0000, v92
	v_mul_f32_e32 v92, v113, v113
	v_mov_b32_e32 v93, v39
	v_pk_fma_f32 v[114:115], v[66:67], v[66:67], v[114:115]
	v_pk_add_f32 v[118:119], v[118:119], v[120:121]
	v_pk_add_f32 v[104:105], v[94:95], v[104:105] op_sel:[1,0] op_sel_hi:[0,1]
	v_pk_add_f32 v[90:91], v[98:99], v[90:91]
; __device__ __forceinline__ float shx(float v, int lane, int off) { return __builtin_bit_cast(float, __builtin_amdgcn_ds_bpermute((lane ^ off) << 2, __builtin_bit_cast(int, v))); }
; __device__ __forceinline__ float wave_sum(float v, int lane) {
; #pragma unroll
;     for (int o = 1; o < 64; o <<= 1) v += shx(v, lane, o);
;     return v;
; __device__ __forceinline__ void rms_rows2_b2f(const bf16* x0, const bf16* x1, const float* g, float* o0, float* o1, int lane) {
;     ...
;     const float rs = 1.f / sqrtf(wave_sum(s, lane) * (1.f / D) + NORM_EPS), rt = 1.f / sqrtf(wave_sum(t, lane) * (1.f / D) + NORM_EPS);
;     f32x4* p0 = (f32x4*)o0 + 2 * lane; f32x4* p1 = (f32x4*)o1 + 2 * lane;
; #pragma unroll
;     for (int j = 0; j < 4; ++j) { const f32x4 ga = gr[128 * j], gb = gr[128 * j + 1];
;         p0[128 * j]     = (f32x4){bflo(v[j].x), bfhi(v[j].x), bflo(v[j].y), bfhi(v[j].y)} * rs * ga; p0[128 * j + 1] = (f32x4){bflo(v[j].z), bfhi(v[j].z), bflo(v[j].w), bfhi(v[j].w)} * rs * gb;
;         p1[128 * j]     = (f32x4){bflo(w[j].x), bfhi(w[j].x), bflo(w[j].y), bfhi(w[j].y)} * rt * ga; p1[128 * j + 1] = (f32x4){bflo(w[j].z), bfhi(w[j].z), bflo(w[j].w), bfhi(w[j].w)} * rt * gb; }
	v_pk_add_f32 v[98:99], v[116:117], v[102:103] op_sel:[1,0] op_sel_hi:[0,1]
	v_pk_mul_f32 v[96:97], v[24:25], v[96:97]
	v_pk_fma_f32 v[122:123], v[28:29], v[28:29], v[122:123]
	v_mul_f32_e32 v137, v32, v32
	v_mul_f32_e32 v138, v33, v33
	v_mov_b32_e32 v128, v109
	v_mov_b32_e32 v129, v111
	v_pk_fma_f32 v[124:125], v[68:69], v[68:69], v[124:125]
	v_pk_fma_f32 v[120:121], v[40:41], v[40:41], v[126:127]
	v_pk_fma_f32 v[126:127], v[54:55], v[54:55], v[34:35] op_sel_hi:[1,1,0]
	v_pk_fma_f32 v[130:131], v[56:57], v[56:57], v[38:39] op_sel_hi:[1,1,0]
	v_pk_fma_f32 v[134:135], v[112:113], v[112:113], v[92:93] op_sel_hi:[1,1,0]
	v_mov_b32_e32 v109, v110
	v_pk_add_f32 v[110:111], v[114:115], v[114:115] op_sel:[0,1] op_sel_hi:[1,0]
	v_pk_add_f32 v[88:89], v[88:89], v[118:119]
	v_pk_add_f32 v[94:95], v[94:95], v[104:105]
	v_mov_b32_e32 v99, v136
	v_mov_b32_e32 v91, v97
	v_mov_b32_e32 v127, v137
	v_mov_b32_e32 v131, v138
	v_mov_b32_e32 v38, v134
	v_pk_add_f32 v[104:105], v[124:125], v[110:111]
	v_pk_add_f32 v[88:89], v[122:123], v[88:89]
	v_mov_b32_e32 v92, v94
	v_pk_add_f32 v[90:91], v[90:91], v[98:99]
	v_mul_f32_e32 v139, v35, v35
	v_pk_mul_f32 v[132:133], v[46:47], v[46:47]
	v_pk_add_f32 v[110:111], v[126:127], v[130:131]
	v_pk_add_f32 v[94:95], v[134:135], v[94:95]
	v_pk_add_f32 v[104:105], v[124:125], v[104:105] op_sel:[1,0] op_sel_hi:[0,1]
	v_pk_mul_f32 v[92:93], v[38:39], v[92:93]
	v_pk_add_f32 v[88:89], v[90:91], v[88:89]
	v_pk_fma_f32 v[102:103], v[42:43], v[42:43], v[132:133]
	v_pk_add_f32 v[96:97], v[120:121], v[110:111]
	v_mov_b32_e32 v105, v139
	v_mov_b32_e32 v95, v93
	v_add_f32_e32 v20, v88, v89
	v_pk_add_f32 v[96:97], v[102:103], v[96:97]
	v_pk_add_f32 v[88:89], v[94:95], v[104:105]
	ds_bpermute_b32 v24, v80, v20
	v_pk_add_f32 v[88:89], v[88:89], v[96:97]
	s_waitcnt lgkmcnt(0)
	v_add_f32_e32 v20, v20, v24
	v_add_f32_e32 v34, v88, v89
	ds_bpermute_b32 v38, v80, v34
	ds_bpermute_b32 v24, v81, v20
	s_waitcnt lgkmcnt(1)
	v_add_f32_e32 v34, v34, v38
	ds_bpermute_b32 v38, v81, v34
	s_waitcnt lgkmcnt(1)
	v_add_f32_e32 v20, v20, v24
	ds_bpermute_b32 v24, v82, v20
	s_waitcnt lgkmcnt(1)
	v_add_f32_e32 v34, v34, v38
	ds_bpermute_b32 v38, v82, v34
	s_waitcnt lgkmcnt(1)
	v_add_f32_e32 v20, v20, v24
	ds_bpermute_b32 v24, v83, v20
	s_waitcnt lgkmcnt(1)
	v_add_f32_e32 v34, v34, v38
	ds_bpermute_b32 v38, v83, v34
	s_waitcnt lgkmcnt(1)
	v_add_f32_e32 v20, v20, v24
	ds_bpermute_b32 v24, v84, v20
	s_waitcnt lgkmcnt(1)
	v_add_f32_e32 v34, v34, v38
	ds_bpermute_b32 v38, v84, v34
	s_waitcnt lgkmcnt(1)
	v_add_f32_e32 v20, v20, v24
	ds_bpermute_b32 v24, v85, v20
	s_waitcnt lgkmcnt(1)
	v_add_f32_e32 v34, v34, v38
	ds_bpermute_b32 v38, v85, v34
	s_waitcnt lgkmcnt(1)
	v_add_f32_e32 v20, v20, v24
	v_fmamk_f32 v20, v20, 0x3a000000, v86
	v_mul_f32_e32 v24, 0x4f800000, v20
	v_cmp_gt_f32_e32 vcc, s17, v20
	s_waitcnt lgkmcnt(0)
	v_add_f32_e32 v34, v34, v38
	v_cndmask_b32_e32 v20, v20, v24, vcc
	v_fmamk_f32 v24, v34, 0x3a000000, v86
	v_sqrt_f32_e32 v34, v20
	v_mul_f32_e32 v38, 0x4f800000, v24
	v_cmp_gt_f32_e64 s[0:1], s17, v24
	v_add_u32_e32 v88, -1, v34
	s_nop 0
	v_cndmask_b32_e64 v24, v24, v38, s[0:1]
	v_sqrt_f32_e32 v38, v24
	v_add_u32_e32 v89, 1, v34
	v_fma_f32 v90, -v88, v34, v20
	v_fma_f32 v91, -v89, v34, v20
	v_cmp_ge_f32_e64 s[2:3], 0, v90
	v_add_u32_e32 v90, 1, v38
	s_nop 0
	v_cndmask_b32_e64 v34, v34, v88, s[2:3]
	v_add_u32_e32 v88, -1, v38
	v_cmp_lt_f32_e64 s[2:3], 0, v91
	v_fma_f32 v91, -v90, v38, v24
	s_nop 0
	v_cndmask_b32_e64 v34, v34, v89, s[2:3]
	v_fma_f32 v89, -v88, v38, v24
	v_cmp_ge_f32_e64 s[2:3], 0, v89
	v_mul_f32_e32 v92, 0x37800000, v34
	v_cndmask_b32_e32 v34, v34, v92, vcc
	v_cndmask_b32_e64 v38, v38, v88, s[2:3]
	v_cmp_lt_f32_e64 s[2:3], 0, v91
	v_cmp_class_f32_e32 vcc, v20, v87
	s_nop 0
	v_cndmask_b32_e64 v38, v38, v90, s[2:3]
	v_cndmask_b32_e32 v20, v34, v20, vcc
	v_mul_f32_e32 v34, 0x37800000, v38
	v_div_scale_f32 v88, s[2:3], v20, v20, 1.0
	v_cndmask_b32_e64 v34, v38, v34, s[0:1]
	v_cmp_class_f32_e64 s[0:1], v24, v87
	v_rcp_f32_e32 v38, v88
	v_div_scale_f32 v89, vcc, 1.0, v20, 1.0
	v_cndmask_b32_e64 v34, v34, v24, s[0:1]
	v_div_scale_f32 v90, s[0:1], v34, v34, 1.0
	v_rcp_f32_e32 v92, v90
	v_fma_f32 v24, -v88, v38, 1.0
	v_fmac_f32_e32 v38, v24, v38
	v_mul_f32_e32 v24, v89, v38
	v_fma_f32 v93, -v90, v92, 1.0
	v_div_scale_f32 v91, s[0:1], 1.0, v34, 1.0
	v_fma_f32 v94, -v88, v24, v89
	v_fmac_f32_e32 v92, v93, v92
	v_fmac_f32_e32 v24, v94, v38
	v_mul_f32_e32 v93, v91, v92
	v_fma_f32 v88, -v88, v24, v89
	v_fma_f32 v89, -v90, v93, v91
	v_div_fmas_f32 v24, v88, v38, v24
	v_fmac_f32_e32 v93, v89, v92
	v_div_fixup_f32 v24, v24, v20, 1.0
	v_fma_f32 v20, -v90, v93, v91
	s_mov_b64 vcc, s[0:1]
	v_div_fmas_f32 v20, v20, v92, v93
	v_pk_mul_f32 v[88:89], v[24:25], v[100:101] op_sel_hi:[0,1]
	v_pk_mul_f32 v[74:75], v[24:25], v[74:75] op_sel_hi:[0,1]
	v_pk_mul_f32 v[92:93], v[24:25], v[76:77] op_sel_hi:[0,1]
	v_pk_mul_f32 v[78:79], v[24:25], v[78:79] op_sel_hi:[0,1]
	v_div_fixup_f32 v38, v20, v34, 1.0
	v_pk_mul_f32 v[76:77], v[6:7], v[74:75]
	v_pk_mul_f32 v[74:75], v[4:5], v[88:89]
	v_pk_mul_f32 v[90:91], v[2:3], v[78:79]
	v_pk_mul_f32 v[88:89], v[0:1], v[92:93]
	global_store_dwordx4 v[52:53], v[74:77], off nt
	global_store_dwordx4 v[52:53], v[88:91], off offset:16 nt
	v_pk_mul_f32 v[78:79], v[38:39], v[108:109] op_sel_hi:[0,1]
	v_pk_mul_f32 v[74:75], v[38:39], v[128:129] op_sel_hi:[0,1]
	v_pk_mul_f32 v[76:77], v[38:39], v[106:107] op_sel_hi:[0,1]
	v_pk_mul_f32 v[88:89], v[38:39], v[112:113] op_sel_hi:[0,1]
	v_pk_mul_f32 v[6:7], v[6:7], v[76:77]
	v_pk_mul_f32 v[4:5], v[4:5], v[74:75]
	v_pk_mul_f32 v[2:3], v[2:3], v[88:89]
	v_pk_mul_f32 v[0:1], v[0:1], v[78:79]
	global_store_dwordx4 v[44:45], v[4:7], off nt
	global_store_dwordx4 v[44:45], v[0:3], off offset:16 nt
	global_load_dwordx4 v[0:3], v[10:11], off offset:2048
	s_nop 0
	global_load_dwordx4 v[4:7], v[10:11], off offset:2064
	v_mov_b32_e32 v74, v59
	v_mov_b32_e32 v75, v63
	v_mov_b32_e32 v59, v62
	v_mov_b32_e32 v76, v61
	v_mov_b32_e32 v77, v65
	v_mov_b32_e32 v61, v64
	v_mov_b32_e32 v62, v67
	v_mov_b32_e32 v63, v71
	v_mov_b32_e32 v64, v69
	v_mov_b32_e32 v65, v73
	v_mov_b32_e32 v67, v70
	v_mov_b32_e32 v69, v72
	v_pk_mul_f32 v[70:71], v[24:25], v[74:75] op_sel_hi:[0,1]
	v_pk_mul_f32 v[58:59], v[24:25], v[58:59] op_sel_hi:[0,1]
	v_pk_mul_f32 v[72:73], v[24:25], v[76:77] op_sel_hi:[0,1]
	v_pk_mul_f32 v[74:75], v[24:25], v[60:61] op_sel_hi:[0,1]
	v_pk_mul_f32 v[76:77], v[38:39], v[62:63] op_sel_hi:[0,1]
	v_pk_mul_f32 v[66:67], v[38:39], v[66:67] op_sel_hi:[0,1]
	v_pk_mul_f32 v[78:79], v[38:39], v[64:65] op_sel_hi:[0,1]
	v_pk_mul_f32 v[68:69], v[38:39], v[68:69] op_sel_hi:[0,1]
	v_pk_mul_f32 v[50:51], v[24:25], v[50:51] op_sel_hi:[0,1]
	v_pk_mul_f32 v[48:49], v[24:25], v[48:49] op_sel_hi:[0,1]
	v_pk_mul_f32 v[56:57], v[38:39], v[56:57] op_sel_hi:[0,1]
	v_mov_b32_e32 v20, v25
	v_mov_b32_e32 v34, v39
	v_pk_mul_f32 v[34:35], v[38:39], v[34:35] op_sel_hi:[0,1]
	s_waitcnt vmcnt(1)
; #define LOCAL_IDS() int tid = threadIdx.x; asm volatile("" : "+v"(tid)); const int lane = tid & 63, wave = __builtin_amdgcn_readfirstlane(tid >> 6), gw = vcu * NWAVES + wave; (void)lane; (void)gw
; __device__ __forceinline__ void rms_rows2_b2f(const bf16* x0, const bf16* x1, const float* g, float* o0, float* o1, int lane) {
;     ...
; #pragma unroll
;     for (int j = 0; j < 4; ++j) { const f32x4 ga = gr[128 * j], gb = gr[128 * j + 1];
;         p0[128 * j]     = (f32x4){bflo(v[j].x), bfhi(v[j].x), bflo(v[j].y), bfhi(v[j].y)} * rs * ga; p0[128 * j + 1] = (f32x4){bflo(v[j].z), bfhi(v[j].z), bflo(v[j].w), bfhi(v[j].w)} * rs * gb;
;         p1[128 * j]     = (f32x4){bflo(w[j].x), bfhi(w[j].x), bflo(w[j].y), bfhi(w[j].y)} * rt * ga; p1[128 * j + 1] = (f32x4){bflo(w[j].z), bfhi(w[j].z), bflo(w[j].w), bfhi(w[j].w)} * rt * gb; }
; __global__ void __launch_bounds__(NWAVES * 64, 2) mega_fwd(Args args) {
;     ...
;     { LOCAL_IDS(); for (int m = gw; m < M / 2; m += NGW) rms_rows2_b2f(XN + (size_t)m * D, XN + (size_t)(m + M / 2) * D, ln_f, out + (size_t)m * D, out + (size_t)(m + M / 2) * D, lane); }
	v_pk_mul_f32 v[58:59], v[0:1], v[58:59]
	v_pk_mul_f32 v[60:61], v[2:3], v[70:71]
	s_waitcnt vmcnt(0)
	v_pk_mul_f32 v[62:63], v[4:5], v[74:75]
	v_pk_mul_f32 v[64:65], v[6:7], v[72:73]
	v_pk_mul_f32 v[0:1], v[0:1], v[66:67]
	v_pk_mul_f32 v[2:3], v[2:3], v[76:77]
	v_pk_mul_f32 v[4:5], v[4:5], v[68:69]
	v_pk_mul_f32 v[6:7], v[6:7], v[78:79]
	global_store_dwordx4 v[52:53], v[58:61], off offset:2048 nt
	global_store_dwordx4 v[52:53], v[62:65], off offset:2064 nt
	global_store_dwordx4 v[44:45], v[0:3], off offset:2048 nt
	global_store_dwordx4 v[44:45], v[4:7], off offset:2064 nt
	global_load_dwordx4 v[0:3], v[12:13], off
	s_nop 0
	global_load_dwordx4 v[4:7], v[12:13], off offset:16
	v_add_co_u32_e32 v58, vcc, s18, v52
	v_mov_b32_e32 v52, v28
	s_nop 0
	v_addc_co_u32_e32 v59, vcc, 0, v53, vcc
	v_mov_b32_e32 v60, v26
	v_mov_b32_e32 v61, v22
	v_mov_b32_e32 v53, v30
	v_mov_b32_e32 v62, v42
	v_mov_b32_e32 v64, v40
	v_mov_b32_e32 v65, v36
	v_mov_b32_e32 v63, v46
	v_add_co_u32_e32 v44, vcc, s18, v44
	v_pk_mul_f32 v[66:67], v[24:25], v[52:53] op_sel_hi:[0,1]
	v_pk_mul_f32 v[52:53], v[24:25], v[60:61] op_sel_hi:[0,1]
	v_pk_mul_f32 v[60:61], v[38:39], v[54:55] op_sel_hi:[0,1]
	v_pk_mul_f32 v[62:63], v[38:39], v[62:63] op_sel_hi:[0,1]
	v_pk_mul_f32 v[64:65], v[38:39], v[64:65] op_sel_hi:[0,1]
	v_addc_co_u32_e32 v45, vcc, 0, v45, vcc
	v_mov_b32_e32 v22, v27
	v_mov_b32_e32 v30, v29
	v_mov_b32_e32 v36, v41
	v_mov_b32_e32 v46, v43
	v_pk_mul_f32 v[26:27], v[24:25], v[18:19] op_sel_hi:[0,1]
	v_pk_mul_f32 v[18:19], v[24:25], v[22:23] op_sel_hi:[0,1]
	v_pk_mul_f32 v[28:29], v[24:25], v[20:21] op_sel_hi:[0,1]
	v_pk_mul_f32 v[22:23], v[24:25], v[30:31] op_sel_hi:[0,1]
	v_pk_mul_f32 v[30:31], v[38:39], v[32:33] op_sel_hi:[0,1]
	v_pk_mul_f32 v[32:33], v[38:39], v[36:37] op_sel_hi:[0,1]
	v_pk_mul_f32 v[36:37], v[38:39], v[46:47] op_sel_hi:[0,1]
	s_waitcnt vmcnt(1)
	v_pk_mul_f32 v[48:49], v[48:49], v[0:1]
	v_pk_mul_f32 v[50:51], v[50:51], v[2:3]
	s_waitcnt vmcnt(0)
	v_pk_mul_f32 v[52:53], v[52:53], v[4:5]
	v_pk_mul_f32 v[54:55], v[66:67], v[6:7]
	v_pk_mul_f32 v[0:1], v[60:61], v[0:1]
	v_pk_mul_f32 v[2:3], v[56:57], v[2:3]
	v_pk_mul_f32 v[4:5], v[64:65], v[4:5]
	v_pk_mul_f32 v[6:7], v[62:63], v[6:7]
	global_store_dwordx4 v[58:59], v[48:51], off nt
	global_store_dwordx4 v[58:59], v[52:55], off offset:16 nt
	global_store_dwordx4 v[44:45], v[0:3], off nt
	global_store_dwordx4 v[44:45], v[4:7], off offset:16 nt
	global_load_dwordx4 v[0:3], v[14:15], off
	s_nop 0
	global_load_dwordx4 v[4:7], v[14:15], off offset:16
	s_waitcnt vmcnt(1)
	v_pk_mul_f32 v[18:19], v[18:19], v[0:1]
	v_pk_mul_f32 v[20:21], v[26:27], v[2:3]
	s_waitcnt vmcnt(0)
	v_pk_mul_f32 v[22:23], v[22:23], v[4:5]
	v_pk_mul_f32 v[24:25], v[28:29], v[6:7]
	v_pk_mul_f32 v[0:1], v[32:33], v[0:1]
	v_pk_mul_f32 v[2:3], v[30:31], v[2:3]
	v_pk_mul_f32 v[4:5], v[36:37], v[4:5]
	v_pk_mul_f32 v[6:7], v[34:35], v[6:7]
	global_store_dwordx4 v[58:59], v[18:21], off offset:2048 nt
	global_store_dwordx4 v[58:59], v[22:25], off offset:2064 nt
	global_store_dwordx4 v[44:45], v[0:3], off offset:2048 nt
	global_store_dwordx4 v[44:45], v[4:7], off offset:2064 nt
	s_cbranch_scc0 .LBB0_1473
